# v120: P0 M-matrix cos/sin sum loops software-prefetched (w_f loads one iteration ahead, two register sets)
# speedup vs baseline: 1.0051x; 1.0051x over previous
.LBB0_44:
	v_lshrrev_b32_e32 v6, 7, v4
	v_and_b32_e32 v0, 0xc07f, v4
	v_lshlrev_b32_e32 v7, 3, v6
	v_lshlrev_b32_e32 v8, 1, v6
	v_lshl_add_u32 v9, v6, 1, v6
	v_lshlrev_b32_e32 v10, 2, v6
	v_lshl_add_u32 v11, v6, 2, v6
	v_mul_lo_u32 v12, v6, 6
	v_mul_lo_u32 v13, v6, 7
	v_cmp_lt_u32_e32 vcc, s33, v4
	v_lshlrev_b32_e32 v0, 2, v0
	s_and_saveexec_b64 s[28:29], vcc
	s_xor_b64 s[28:29], exec, s[28:29]
	s_cbranch_execz .LBB0_48
	v_lshl_add_u64 v[2:3], s[24:25], 0, v[0:1]
	v_mov_b32_e32 v0, 0
	s_mov_b64 s[30:31], 0
	v_mov_b32_e32 v14, 0
	v_lshl_add_u64 v[48:49], v[2:3], 0, s[30:31]
	global_load_dword v31, v[48:49], off
	global_load_dword v32, v[48:49], off offset:512
	global_load_dword v33, v[48:49], off offset:1024
	global_load_dword v34, v[48:49], off offset:1536
	global_load_dword v35, v[48:49], off offset:2048
	global_load_dword v36, v[48:49], off offset:2560
	global_load_dword v37, v[48:49], off offset:3072
	global_load_dword v38, v[48:49], off offset:3584
	s_add_u32 s30, s30, 0x1000
	s_addc_u32 s31, s31, 0
.LBB0_46:
	v_lshl_add_u64 v[48:49], v[2:3], 0, s[30:31]
	global_load_dword v39, v[48:49], off
	global_load_dword v40, v[48:49], off offset:512
	global_load_dword v41, v[48:49], off offset:1024
	global_load_dword v42, v[48:49], off offset:1536
	global_load_dword v43, v[48:49], off offset:2048
	global_load_dword v44, v[48:49], off offset:2560
	global_load_dword v45, v[48:49], off offset:3072
	global_load_dword v46, v[48:49], off offset:3584
	s_add_u32 s30, s30, 0x1000
	s_addc_u32 s31, s31, 0
	v_and_b32_e32 v17, 0x78, v14
	v_add_u32_e32 v24, v6, v14
	v_add_u32_e32 v25, v8, v14
	v_cvt_f32_ubyte0_e32 v17, v17
	v_and_b32_e32 v24, 0x7f, v24
	v_add_u32_e32 v26, v9, v14
	v_and_b32_e32 v25, 0x7e, v25
	v_mul_f32_e32 v17, 0x3c000000, v17
	v_cvt_f32_ubyte0_e32 v24, v24
	v_add_u32_e32 v27, v10, v14
	v_and_b32_e32 v26, 0x7f, v26
	v_cvt_f32_ubyte0_e32 v25, v25
	v_sin_f32_e32 v17, v17
	v_mul_f32_e32 v24, 0x3c000000, v24
	v_add_u32_e32 v28, v11, v14
	v_and_b32_e32 v27, 0x7c, v27
	v_cvt_f32_ubyte0_e32 v26, v26
	v_mul_f32_e32 v25, 0x3c000000, v25
	v_sin_f32_e32 v24, v24
	v_add_u32_e32 v29, v12, v14
	v_and_b32_e32 v28, 0x7f, v28
	v_cvt_f32_ubyte0_e32 v27, v27
	v_mul_f32_e32 v26, 0x3c000000, v26
	v_sin_f32_e32 v25, v25
	v_add_u32_e32 v30, v13, v14
	v_and_b32_e32 v29, 0x7e, v29
	v_cvt_f32_ubyte0_e32 v28, v28
	v_mul_f32_e32 v27, 0x3c000000, v27
	v_sin_f32_e32 v26, v26
	v_and_b32_e32 v30, 0x7f, v30
	v_cvt_f32_ubyte0_e32 v29, v29
	v_mul_f32_e32 v28, 0x3c000000, v28
	v_sin_f32_e32 v27, v27
	v_cvt_f32_ubyte0_e32 v30, v30
	v_mul_f32_e32 v29, 0x3c000000, v29
	v_sin_f32_e32 v28, v28
	v_mul_f32_e32 v30, 0x3c000000, v30
	v_sin_f32_e32 v29, v29
	v_sin_f32_e32 v30, v30
	v_add_u32_e32 v14, v14, v7
	s_waitcnt vmcnt(15)
	v_fmac_f32_e32 v0, v17, v31
	s_waitcnt vmcnt(14)
	v_fmac_f32_e32 v0, v24, v32
	s_waitcnt vmcnt(13)
	v_fmac_f32_e32 v0, v25, v33
	s_waitcnt vmcnt(12)
	v_fmac_f32_e32 v0, v26, v34
	s_waitcnt vmcnt(11)
	v_fmac_f32_e32 v0, v27, v35
	s_waitcnt vmcnt(10)
	v_fmac_f32_e32 v0, v28, v36
	s_waitcnt vmcnt(9)
	v_fmac_f32_e32 v0, v29, v37
	s_waitcnt vmcnt(8)
	v_fmac_f32_e32 v0, v30, v38
	v_lshl_add_u64 v[48:49], v[2:3], 0, s[30:31]
	global_load_dword v31, v[48:49], off
	global_load_dword v32, v[48:49], off offset:512
	global_load_dword v33, v[48:49], off offset:1024
	global_load_dword v34, v[48:49], off offset:1536
	global_load_dword v35, v[48:49], off offset:2048
	global_load_dword v36, v[48:49], off offset:2560
	global_load_dword v37, v[48:49], off offset:3072
	global_load_dword v38, v[48:49], off offset:3584
	s_add_u32 s30, s30, 0x1000
	s_addc_u32 s31, s31, 0
	v_and_b32_e32 v17, 0x78, v14
	v_add_u32_e32 v24, v6, v14
	v_add_u32_e32 v25, v8, v14
	v_cvt_f32_ubyte0_e32 v17, v17
	v_and_b32_e32 v24, 0x7f, v24
	v_add_u32_e32 v26, v9, v14
	v_and_b32_e32 v25, 0x7e, v25
	v_mul_f32_e32 v17, 0x3c000000, v17
	v_cvt_f32_ubyte0_e32 v24, v24
	v_add_u32_e32 v27, v10, v14
	v_and_b32_e32 v26, 0x7f, v26
	v_cvt_f32_ubyte0_e32 v25, v25
	v_sin_f32_e32 v17, v17
	v_mul_f32_e32 v24, 0x3c000000, v24
	v_add_u32_e32 v28, v11, v14
	v_and_b32_e32 v27, 0x7c, v27
	v_cvt_f32_ubyte0_e32 v26, v26
	v_mul_f32_e32 v25, 0x3c000000, v25
	v_sin_f32_e32 v24, v24
	v_add_u32_e32 v29, v12, v14
	v_and_b32_e32 v28, 0x7f, v28
	v_cvt_f32_ubyte0_e32 v27, v27
	v_mul_f32_e32 v26, 0x3c000000, v26
	v_sin_f32_e32 v25, v25
	v_add_u32_e32 v30, v13, v14
	v_and_b32_e32 v29, 0x7e, v29
	v_cvt_f32_ubyte0_e32 v28, v28
	v_mul_f32_e32 v27, 0x3c000000, v27
	v_sin_f32_e32 v26, v26
	v_and_b32_e32 v30, 0x7f, v30
	v_cvt_f32_ubyte0_e32 v29, v29
	v_mul_f32_e32 v28, 0x3c000000, v28
	v_sin_f32_e32 v27, v27
	v_cvt_f32_ubyte0_e32 v30, v30
	v_mul_f32_e32 v29, 0x3c000000, v29
	v_sin_f32_e32 v28, v28
	v_mul_f32_e32 v30, 0x3c000000, v30
	v_sin_f32_e32 v29, v29
	v_sin_f32_e32 v30, v30
	v_add_u32_e32 v14, v14, v7
	s_cmp_eq_u32 s30, 0xf000
	s_waitcnt vmcnt(15)
	v_fmac_f32_e32 v0, v17, v39
	s_waitcnt vmcnt(14)
	v_fmac_f32_e32 v0, v24, v40
	s_waitcnt vmcnt(13)
	v_fmac_f32_e32 v0, v25, v41
	s_waitcnt vmcnt(12)
	v_fmac_f32_e32 v0, v26, v42
	s_waitcnt vmcnt(11)
	v_fmac_f32_e32 v0, v27, v43
	s_waitcnt vmcnt(10)
	v_fmac_f32_e32 v0, v28, v44
	s_waitcnt vmcnt(9)
	v_fmac_f32_e32 v0, v29, v45
	s_waitcnt vmcnt(8)
	v_fmac_f32_e32 v0, v30, v46
	s_cbranch_scc0 .LBB0_46
	v_lshl_add_u64 v[48:49], v[2:3], 0, s[30:31]
	global_load_dword v39, v[48:49], off
	global_load_dword v40, v[48:49], off offset:512
	global_load_dword v41, v[48:49], off offset:1024
	global_load_dword v42, v[48:49], off offset:1536
	global_load_dword v43, v[48:49], off offset:2048
	global_load_dword v44, v[48:49], off offset:2560
	global_load_dword v45, v[48:49], off offset:3072
	global_load_dword v46, v[48:49], off offset:3584
	s_add_u32 s30, s30, 0x1000
	s_addc_u32 s31, s31, 0
	v_and_b32_e32 v17, 0x78, v14
	v_add_u32_e32 v24, v6, v14
	v_add_u32_e32 v25, v8, v14
	v_cvt_f32_ubyte0_e32 v17, v17
	v_and_b32_e32 v24, 0x7f, v24
	v_add_u32_e32 v26, v9, v14
	v_and_b32_e32 v25, 0x7e, v25
	v_mul_f32_e32 v17, 0x3c000000, v17
	v_cvt_f32_ubyte0_e32 v24, v24
	v_add_u32_e32 v27, v10, v14
	v_and_b32_e32 v26, 0x7f, v26
	v_cvt_f32_ubyte0_e32 v25, v25
	v_sin_f32_e32 v17, v17
	v_mul_f32_e32 v24, 0x3c000000, v24
	v_add_u32_e32 v28, v11, v14
	v_and_b32_e32 v27, 0x7c, v27
	v_cvt_f32_ubyte0_e32 v26, v26
	v_mul_f32_e32 v25, 0x3c000000, v25
	v_sin_f32_e32 v24, v24
	v_add_u32_e32 v29, v12, v14
	v_and_b32_e32 v28, 0x7f, v28
	v_cvt_f32_ubyte0_e32 v27, v27
	v_mul_f32_e32 v26, 0x3c000000, v26
	v_sin_f32_e32 v25, v25
	v_add_u32_e32 v30, v13, v14
	v_and_b32_e32 v29, 0x7e, v29
	v_cvt_f32_ubyte0_e32 v28, v28
	v_mul_f32_e32 v27, 0x3c000000, v27
	v_sin_f32_e32 v26, v26
	v_and_b32_e32 v30, 0x7f, v30
	v_cvt_f32_ubyte0_e32 v29, v29
	v_mul_f32_e32 v28, 0x3c000000, v28
	v_sin_f32_e32 v27, v27
	v_cvt_f32_ubyte0_e32 v30, v30
	v_mul_f32_e32 v29, 0x3c000000, v29
	v_sin_f32_e32 v28, v28
	v_mul_f32_e32 v30, 0x3c000000, v30
	v_sin_f32_e32 v29, v29
	v_sin_f32_e32 v30, v30
	v_add_u32_e32 v14, v14, v7
	s_waitcnt vmcnt(15)
	v_fmac_f32_e32 v0, v17, v31
	s_waitcnt vmcnt(14)
	v_fmac_f32_e32 v0, v24, v32
	s_waitcnt vmcnt(13)
	v_fmac_f32_e32 v0, v25, v33
	s_waitcnt vmcnt(12)
	v_fmac_f32_e32 v0, v26, v34
	s_waitcnt vmcnt(11)
	v_fmac_f32_e32 v0, v27, v35
	s_waitcnt vmcnt(10)
	v_fmac_f32_e32 v0, v28, v36
	s_waitcnt vmcnt(9)
	v_fmac_f32_e32 v0, v29, v37
	s_waitcnt vmcnt(8)
	v_fmac_f32_e32 v0, v30, v38
	v_and_b32_e32 v17, 0x78, v14
	v_add_u32_e32 v24, v6, v14
	v_add_u32_e32 v25, v8, v14
	v_cvt_f32_ubyte0_e32 v17, v17
	v_and_b32_e32 v24, 0x7f, v24
	v_add_u32_e32 v26, v9, v14
	v_and_b32_e32 v25, 0x7e, v25
	v_mul_f32_e32 v17, 0x3c000000, v17
	v_cvt_f32_ubyte0_e32 v24, v24
	v_add_u32_e32 v27, v10, v14
	v_and_b32_e32 v26, 0x7f, v26
	v_cvt_f32_ubyte0_e32 v25, v25
	v_sin_f32_e32 v17, v17
	v_mul_f32_e32 v24, 0x3c000000, v24
	v_add_u32_e32 v28, v11, v14
	v_and_b32_e32 v27, 0x7c, v27
	v_cvt_f32_ubyte0_e32 v26, v26
	v_mul_f32_e32 v25, 0x3c000000, v25
	v_sin_f32_e32 v24, v24
	v_add_u32_e32 v29, v12, v14
	v_and_b32_e32 v28, 0x7f, v28
	v_cvt_f32_ubyte0_e32 v27, v27
	v_mul_f32_e32 v26, 0x3c000000, v26
	v_sin_f32_e32 v25, v25
	v_add_u32_e32 v30, v13, v14
	v_and_b32_e32 v29, 0x7e, v29
	v_cvt_f32_ubyte0_e32 v28, v28
	v_mul_f32_e32 v27, 0x3c000000, v27
	v_sin_f32_e32 v26, v26
	v_and_b32_e32 v30, 0x7f, v30
	v_cvt_f32_ubyte0_e32 v29, v29
	v_mul_f32_e32 v28, 0x3c000000, v28
	v_sin_f32_e32 v27, v27
	v_cvt_f32_ubyte0_e32 v30, v30
	v_mul_f32_e32 v29, 0x3c000000, v29
	v_sin_f32_e32 v28, v28
	v_mul_f32_e32 v30, 0x3c000000, v30
	v_sin_f32_e32 v29, v29
	v_sin_f32_e32 v30, v30
	v_add_u32_e32 v14, v14, v7
	s_waitcnt vmcnt(7)
	v_fmac_f32_e32 v0, v17, v39
	s_waitcnt vmcnt(6)
	v_fmac_f32_e32 v0, v24, v40
	s_waitcnt vmcnt(5)
	v_fmac_f32_e32 v0, v25, v41
	s_waitcnt vmcnt(4)
	v_fmac_f32_e32 v0, v26, v42
	s_waitcnt vmcnt(3)
	v_fmac_f32_e32 v0, v27, v43
	s_waitcnt vmcnt(2)
	v_fmac_f32_e32 v0, v28, v44
	s_waitcnt vmcnt(1)
	v_fmac_f32_e32 v0, v29, v45
	s_waitcnt vmcnt(0)
	v_fmac_f32_e32 v0, v30, v46
	v_mul_f32_e32 v6, 0xbdb504f3, v0
	v_lshlrev_b32_sdwa v0, v5, v4 dst_sel:DWORD dst_unused:UNUSED_PAD src0_sel:DWORD src1_sel:WORD_0
	v_lshl_add_u64 v[2:3], s[0:1], 0, v[0:1]
	v_add_co_u32_e32 v2, vcc, 0x40000, v2
	s_nop 1
	v_addc_co_u32_e32 v3, vcc, 0, v3, vcc
	global_store_dword v[2:3], v6, off
.LBB0_48:
	s_andn2_saveexec_b64 s[28:29], s[28:29]
	s_cbranch_execz .LBB0_43
	v_lshl_add_u64 v[2:3], s[24:25], 0, v[0:1]
	v_mov_b32_e32 v0, 0
	s_mov_b64 s[30:31], 0
	v_mov_b32_e32 v14, 0
	v_lshl_add_u64 v[48:49], v[2:3], 0, s[30:31]
	global_load_dword v31, v[48:49], off
	global_load_dword v32, v[48:49], off offset:512
	global_load_dword v33, v[48:49], off offset:1024
	global_load_dword v34, v[48:49], off offset:1536
	global_load_dword v35, v[48:49], off offset:2048
	global_load_dword v36, v[48:49], off offset:2560
	global_load_dword v37, v[48:49], off offset:3072
	global_load_dword v38, v[48:49], off offset:3584
	s_add_u32 s30, s30, 0x1000
	s_addc_u32 s31, s31, 0
.LBB0_50:
	v_lshl_add_u64 v[48:49], v[2:3], 0, s[30:31]
	global_load_dword v39, v[48:49], off
	global_load_dword v40, v[48:49], off offset:512
	global_load_dword v41, v[48:49], off offset:1024
	global_load_dword v42, v[48:49], off offset:1536
	global_load_dword v43, v[48:49], off offset:2048
	global_load_dword v44, v[48:49], off offset:2560
	global_load_dword v45, v[48:49], off offset:3072
	global_load_dword v46, v[48:49], off offset:3584
	s_add_u32 s30, s30, 0x1000
	s_addc_u32 s31, s31, 0
	v_and_b32_e32 v17, 0x78, v14
	v_add_u32_e32 v24, v6, v14
	v_add_u32_e32 v25, v8, v14
	v_cvt_f32_ubyte0_e32 v17, v17
	v_and_b32_e32 v24, 0x7f, v24
	v_add_u32_e32 v26, v9, v14
	v_and_b32_e32 v25, 0x7e, v25
	v_mul_f32_e32 v17, 0x3c000000, v17
	v_cvt_f32_ubyte0_e32 v24, v24
	v_add_u32_e32 v27, v10, v14
	v_and_b32_e32 v26, 0x7f, v26
	v_cvt_f32_ubyte0_e32 v25, v25
	v_cos_f32_e32 v17, v17
	v_mul_f32_e32 v24, 0x3c000000, v24
	v_add_u32_e32 v28, v11, v14
	v_and_b32_e32 v27, 0x7c, v27
	v_cvt_f32_ubyte0_e32 v26, v26
	v_mul_f32_e32 v25, 0x3c000000, v25
	v_cos_f32_e32 v24, v24
	v_add_u32_e32 v29, v12, v14
	v_and_b32_e32 v28, 0x7f, v28
	v_cvt_f32_ubyte0_e32 v27, v27
	v_mul_f32_e32 v26, 0x3c000000, v26
	v_cos_f32_e32 v25, v25
	v_add_u32_e32 v30, v13, v14
	v_and_b32_e32 v29, 0x7e, v29
	v_cvt_f32_ubyte0_e32 v28, v28
	v_mul_f32_e32 v27, 0x3c000000, v27
	v_cos_f32_e32 v26, v26
	v_and_b32_e32 v30, 0x7f, v30
	v_cvt_f32_ubyte0_e32 v29, v29
	v_mul_f32_e32 v28, 0x3c000000, v28
	v_cos_f32_e32 v27, v27
	v_cvt_f32_ubyte0_e32 v30, v30
	v_mul_f32_e32 v29, 0x3c000000, v29
	v_cos_f32_e32 v28, v28
	v_mul_f32_e32 v30, 0x3c000000, v30
	v_cos_f32_e32 v29, v29
	v_cos_f32_e32 v30, v30
	v_add_u32_e32 v14, v14, v7
	s_waitcnt vmcnt(15)
	v_fmac_f32_e32 v0, v17, v31
	s_waitcnt vmcnt(14)
	v_fmac_f32_e32 v0, v24, v32
	s_waitcnt vmcnt(13)
	v_fmac_f32_e32 v0, v25, v33
	s_waitcnt vmcnt(12)
	v_fmac_f32_e32 v0, v26, v34
	s_waitcnt vmcnt(11)
	v_fmac_f32_e32 v0, v27, v35
	s_waitcnt vmcnt(10)
	v_fmac_f32_e32 v0, v28, v36
	s_waitcnt vmcnt(9)
	v_fmac_f32_e32 v0, v29, v37
	s_waitcnt vmcnt(8)
	v_fmac_f32_e32 v0, v30, v38
	v_lshl_add_u64 v[48:49], v[2:3], 0, s[30:31]
	global_load_dword v31, v[48:49], off
	global_load_dword v32, v[48:49], off offset:512
	global_load_dword v33, v[48:49], off offset:1024
	global_load_dword v34, v[48:49], off offset:1536
	global_load_dword v35, v[48:49], off offset:2048
	global_load_dword v36, v[48:49], off offset:2560
	global_load_dword v37, v[48:49], off offset:3072
	global_load_dword v38, v[48:49], off offset:3584
	s_add_u32 s30, s30, 0x1000
	s_addc_u32 s31, s31, 0
	v_and_b32_e32 v17, 0x78, v14
	v_add_u32_e32 v24, v6, v14
	v_add_u32_e32 v25, v8, v14
	v_cvt_f32_ubyte0_e32 v17, v17
	v_and_b32_e32 v24, 0x7f, v24
	v_add_u32_e32 v26, v9, v14
	v_and_b32_e32 v25, 0x7e, v25
	v_mul_f32_e32 v17, 0x3c000000, v17
	v_cvt_f32_ubyte0_e32 v24, v24
	v_add_u32_e32 v27, v10, v14
	v_and_b32_e32 v26, 0x7f, v26
	v_cvt_f32_ubyte0_e32 v25, v25
	v_cos_f32_e32 v17, v17
	v_mul_f32_e32 v24, 0x3c000000, v24
	v_add_u32_e32 v28, v11, v14
	v_and_b32_e32 v27, 0x7c, v27
	v_cvt_f32_ubyte0_e32 v26, v26
	v_mul_f32_e32 v25, 0x3c000000, v25
	v_cos_f32_e32 v24, v24
	v_add_u32_e32 v29, v12, v14
	v_and_b32_e32 v28, 0x7f, v28
	v_cvt_f32_ubyte0_e32 v27, v27
	v_mul_f32_e32 v26, 0x3c000000, v26
	v_cos_f32_e32 v25, v25
	v_add_u32_e32 v30, v13, v14
	v_and_b32_e32 v29, 0x7e, v29
	v_cvt_f32_ubyte0_e32 v28, v28
	v_mul_f32_e32 v27, 0x3c000000, v27
	v_cos_f32_e32 v26, v26
	v_and_b32_e32 v30, 0x7f, v30
	v_cvt_f32_ubyte0_e32 v29, v29
	v_mul_f32_e32 v28, 0x3c000000, v28
	v_cos_f32_e32 v27, v27
	v_cvt_f32_ubyte0_e32 v30, v30
	v_mul_f32_e32 v29, 0x3c000000, v29
	v_cos_f32_e32 v28, v28
	v_mul_f32_e32 v30, 0x3c000000, v30
	v_cos_f32_e32 v29, v29
	v_cos_f32_e32 v30, v30
	v_add_u32_e32 v14, v14, v7
	s_cmp_eq_u32 s30, 0xf000
	s_waitcnt vmcnt(15)
	v_fmac_f32_e32 v0, v17, v39
	s_waitcnt vmcnt(14)
	v_fmac_f32_e32 v0, v24, v40
	s_waitcnt vmcnt(13)
	v_fmac_f32_e32 v0, v25, v41
	s_waitcnt vmcnt(12)
	v_fmac_f32_e32 v0, v26, v42
	s_waitcnt vmcnt(11)
	v_fmac_f32_e32 v0, v27, v43
	s_waitcnt vmcnt(10)
	v_fmac_f32_e32 v0, v28, v44
	s_waitcnt vmcnt(9)
	v_fmac_f32_e32 v0, v29, v45
	s_waitcnt vmcnt(8)
	v_fmac_f32_e32 v0, v30, v46
	s_cbranch_scc0 .LBB0_50
	v_lshl_add_u64 v[48:49], v[2:3], 0, s[30:31]
	global_load_dword v39, v[48:49], off
	global_load_dword v40, v[48:49], off offset:512
	global_load_dword v41, v[48:49], off offset:1024
	global_load_dword v42, v[48:49], off offset:1536
	global_load_dword v43, v[48:49], off offset:2048
	global_load_dword v44, v[48:49], off offset:2560
	global_load_dword v45, v[48:49], off offset:3072
	global_load_dword v46, v[48:49], off offset:3584
	s_add_u32 s30, s30, 0x1000
	s_addc_u32 s31, s31, 0
	v_and_b32_e32 v17, 0x78, v14
	v_add_u32_e32 v24, v6, v14
	v_add_u32_e32 v25, v8, v14
	v_cvt_f32_ubyte0_e32 v17, v17
	v_and_b32_e32 v24, 0x7f, v24
	v_add_u32_e32 v26, v9, v14
	v_and_b32_e32 v25, 0x7e, v25
	v_mul_f32_e32 v17, 0x3c000000, v17
	v_cvt_f32_ubyte0_e32 v24, v24
	v_add_u32_e32 v27, v10, v14
	v_and_b32_e32 v26, 0x7f, v26
	v_cvt_f32_ubyte0_e32 v25, v25
	v_cos_f32_e32 v17, v17
	v_mul_f32_e32 v24, 0x3c000000, v24
	v_add_u32_e32 v28, v11, v14
	v_and_b32_e32 v27, 0x7c, v27
	v_cvt_f32_ubyte0_e32 v26, v26
	v_mul_f32_e32 v25, 0x3c000000, v25
	v_cos_f32_e32 v24, v24
	v_add_u32_e32 v29, v12, v14
	v_and_b32_e32 v28, 0x7f, v28
	v_cvt_f32_ubyte0_e32 v27, v27
	v_mul_f32_e32 v26, 0x3c000000, v26
	v_cos_f32_e32 v25, v25
	v_add_u32_e32 v30, v13, v14
	v_and_b32_e32 v29, 0x7e, v29
	v_cvt_f32_ubyte0_e32 v28, v28
	v_mul_f32_e32 v27, 0x3c000000, v27
	v_cos_f32_e32 v26, v26
	v_and_b32_e32 v30, 0x7f, v30
	v_cvt_f32_ubyte0_e32 v29, v29
	v_mul_f32_e32 v28, 0x3c000000, v28
	v_cos_f32_e32 v27, v27
	v_cvt_f32_ubyte0_e32 v30, v30
	v_mul_f32_e32 v29, 0x3c000000, v29
	v_cos_f32_e32 v28, v28
	v_mul_f32_e32 v30, 0x3c000000, v30
	v_cos_f32_e32 v29, v29
	v_cos_f32_e32 v30, v30
	v_add_u32_e32 v14, v14, v7
	s_waitcnt vmcnt(15)
	v_fmac_f32_e32 v0, v17, v31
	s_waitcnt vmcnt(14)
	v_fmac_f32_e32 v0, v24, v32
	s_waitcnt vmcnt(13)
	v_fmac_f32_e32 v0, v25, v33
	s_waitcnt vmcnt(12)
	v_fmac_f32_e32 v0, v26, v34
	s_waitcnt vmcnt(11)
	v_fmac_f32_e32 v0, v27, v35
	s_waitcnt vmcnt(10)
	v_fmac_f32_e32 v0, v28, v36
	s_waitcnt vmcnt(9)
	v_fmac_f32_e32 v0, v29, v37
	s_waitcnt vmcnt(8)
	v_fmac_f32_e32 v0, v30, v38
	v_and_b32_e32 v17, 0x78, v14
	v_add_u32_e32 v24, v6, v14
	v_add_u32_e32 v25, v8, v14
	v_cvt_f32_ubyte0_e32 v17, v17
	v_and_b32_e32 v24, 0x7f, v24
	v_add_u32_e32 v26, v9, v14
	v_and_b32_e32 v25, 0x7e, v25
	v_mul_f32_e32 v17, 0x3c000000, v17
	v_cvt_f32_ubyte0_e32 v24, v24
	v_add_u32_e32 v27, v10, v14
	v_and_b32_e32 v26, 0x7f, v26
	v_cvt_f32_ubyte0_e32 v25, v25
	v_cos_f32_e32 v17, v17
	v_mul_f32_e32 v24, 0x3c000000, v24
	v_add_u32_e32 v28, v11, v14
	v_and_b32_e32 v27, 0x7c, v27
	v_cvt_f32_ubyte0_e32 v26, v26
	v_mul_f32_e32 v25, 0x3c000000, v25
	v_cos_f32_e32 v24, v24
	v_add_u32_e32 v29, v12, v14
	v_and_b32_e32 v28, 0x7f, v28
	v_cvt_f32_ubyte0_e32 v27, v27
	v_mul_f32_e32 v26, 0x3c000000, v26
	v_cos_f32_e32 v25, v25
	v_add_u32_e32 v30, v13, v14
	v_and_b32_e32 v29, 0x7e, v29
	v_cvt_f32_ubyte0_e32 v28, v28
	v_mul_f32_e32 v27, 0x3c000000, v27
	v_cos_f32_e32 v26, v26
	v_and_b32_e32 v30, 0x7f, v30
	v_cvt_f32_ubyte0_e32 v29, v29
	v_mul_f32_e32 v28, 0x3c000000, v28
	v_cos_f32_e32 v27, v27
	v_cvt_f32_ubyte0_e32 v30, v30
	v_mul_f32_e32 v29, 0x3c000000, v29
	v_cos_f32_e32 v28, v28
	v_mul_f32_e32 v30, 0x3c000000, v30
	v_cos_f32_e32 v29, v29
	v_cos_f32_e32 v30, v30
	v_add_u32_e32 v14, v14, v7
	s_waitcnt vmcnt(7)
	v_fmac_f32_e32 v0, v17, v39
	s_waitcnt vmcnt(6)
	v_fmac_f32_e32 v0, v24, v40
	s_waitcnt vmcnt(5)
	v_fmac_f32_e32 v0, v25, v41
	s_waitcnt vmcnt(4)
	v_fmac_f32_e32 v0, v26, v42
	s_waitcnt vmcnt(3)
	v_fmac_f32_e32 v0, v27, v43
	s_waitcnt vmcnt(2)
	v_fmac_f32_e32 v0, v28, v44
	s_waitcnt vmcnt(1)
	v_fmac_f32_e32 v0, v29, v45
	s_waitcnt vmcnt(0)
	v_fmac_f32_e32 v0, v30, v46
	v_mul_f32_e32 v0, 0x3db504f3, v0
	v_lshlrev_b32_sdwa v2, v5, v4 dst_sel:DWORD dst_unused:UNUSED_PAD src0_sel:DWORD src1_sel:WORD_0
	global_store_dword v2, v0, s[0:1]
	s_branch .LBB0_43
